# GEMM1 K-loop back-edge rotation: the address SALU block at the loop head moved in front of the loop-back barrier (peeled iteration keeps its own copy)
# baseline (speedup 1.0000x reference)
; #define PG8_STAGE(bufoff, gbase, voff) do { _Pragma("unroll") for (int _i = 0; _i < 2; ++_i) \
;         __builtin_amdgcn_global_load_lds((const unsigned*)((const char*)(gbase) + (voff)[_i]), (LAS unsigned*)(lds + (bufoff) + ldsw + _i * 8192), 16, 0, 0); } while (0)
; #define PG8_LDA(dst, b, h) do { _Pragma("unroll") for (int m = 0; m < 4; ++m) _Pragma("unroll") for (int k = 0; k < 2; ++k) dst[m][k] = *(const LAS bf16x8*)(lds + PG8_SA(b, h) + aoff + m * 2048 + k * 1024); } while (0)
; #define PG8_LDB(dst, b, h) do { _Pragma("unroll") for (int n = 0; n < 2; ++n) _Pragma("unroll") for (int k = 0; k < 2; ++k) dst[n][k] = *(const LAS bf16x8*)(lds + PG8_SB(b, h) + boff + n * 2048 + k * 1024); } while (0)
; #define PG8_MMA(ai, bj, At, Bt_) do { __builtin_amdgcn_s_setprio(1); _Pragma("unroll") for (int m = 0; m < 4; ++m) _Pragma("unroll") for (int n = 0; n < 2; ++n) _Pragma("unroll") for (int k = 0; k < 2; ++k) \
;         acc[ai][bj][m][n] = __builtin_amdgcn_mfma_f32_16x16x32_bf16(Bt_[n][k], At[m][k], acc[ai][bj][m][n], 0, 0, 0); __builtin_amdgcn_s_setprio(0); } while (0)
; #define PG8_WAIT_L(n) asm volatile("s_waitcnt lgkmcnt(" #n ")" ::: "memory")
; #define PG8_BAR __builtin_amdgcn_s_barrier()
; #define PG8_SCHED __builtin_amdgcn_sched_barrier(0)
; template <bool REMAP>
; DI void gemm_phase(LAS unsigned char* lds, const u16* A, int lda, const u16* Bt, int K, u16* O, int ldc, int nunits) {
;     ...
;         const bool has_next = next_unit(ui + 1, nunits, nxt);
;         const char* nA = has_next ? (const char*)A + (size_t)nxt.pm * tstepA : cA; const char* nB = has_next ? (const char*)Bt + (size_t)nxt.pn * tstepB : cB;
;         for (int t = 0; t < nt; t += 2) {
;             const bool last = (t == nt - 2);
;             const char* a1 = cA + akb(t + 1);
;             const char* a2 = last ? nA + akb(0) : cA + akb(t + 2); const char* b2 = last ? nB : cB + (size_t)(t + 2) * kstep;
;             const char* a3 = last ? nA + akb(1) : cA + akb(t + 3); const char* b3 = b2 + kstep;
;             PG8_LDB(B0, 0, 0); PG8_SCHED; PG8_LDA(At, 0, 0); PG8_STAGE(PG8_SA(1, 1), a1 + hstepA, voffA);
;             PG8_WAIT_L(8); PG8_BAR; PG8_WAIT_L(0); PG8_MMA(0, 0, At, B0); PG8_BAR; PG8_SCHED;
;             PG8_LDB(B1, 0, 1); PG8_STAGE(PG8_SB(0, 0), b2, voffB);
;             PG8_BAR; PG8_WAIT_L(0); PG8_MMA(0, 1, At, B1); PG8_BAR;
.LBB0_136:
	s_ashr_i32 s5, s4, 31
	s_lshl_b64 s[12:13], s[4:5], 19
	s_add_u32 s12, s3, s12
	s_addc_u32 s13, s24, s13
	s_and_b64 s[14:15], s[22:23], exec
	s_cselect_b32 s5, s13, s11
	s_cselect_b32 s46, s12, s10
	s_ashr_i32 s7, s6, 31
	s_lshl_b64 s[14:15], s[6:7], 19
	s_add_u32 s14, s16, s14
	s_addc_u32 s15, s25, s15
	s_and_b64 s[22:23], s[22:23], exec
	s_cselect_b32 s7, s15, s21
	s_cselect_b32 s47, s14, s20
	s_add_u32 s49, s46, 0x80
	s_addc_u32 s50, s5, 0
	s_add_u32 s51, s20, 0x100
	s_addc_u32 s54, s21, 0
	s_add_u32 s22, s10, 0x40080
	s_addc_u32 s23, s11, 0
	s_mov_b32 s55, -2
	s_mov_b64 s[20:21], 0
	v_lshl_add_u64 v[140:141], s[22:23], 0, v[136:137]
	v_lshl_add_u64 v[142:143], s[22:23], 0, v[138:139]
	s_add_u32 s22, s10, s20
	s_addc_u32 s23, s11, s21
	s_add_u32 s30, s22, 0x100
	s_addc_u32 s31, s23, 0
	s_add_u32 s56, s51, s20
	s_addc_u32 s57, s54, s21
	s_add_u32 s22, s22, 0x180
	s_addc_u32 s23, s23, 0
	s_add_i32 s58, 0, 0x10000
	v_add_u32_e32 v160, s58, v145
	ds_read_b128 v[148:151], v160
	ds_read_b128 v[152:155], v160 offset:1024
	ds_read_b128 v[156:159], v160 offset:2048
	ds_read_b128 v[160:163], v160 offset:3072
	s_cmpk_eq_i32 s20, 0x700
	s_cselect_b32 s29, s50, s23
	s_cselect_b32 s28, s49, s22
	s_cselect_b32 s23, s7, s57
	s_cselect_b32 s22, s47, s56
	s_cselect_b32 s31, s5, s31
	s_cselect_b32 s30, s46, s30
	v_lshl_add_u64 v[172:173], v[142:143], 0, s[20:21]
	s_add_i32 m0, s27, 0xc000
	ds_read_b128 v[164:167], v147
	ds_read_b128 v[168:171], v147 offset:1024
	ds_read_b128 v[192:195], v147 offset:2048
	ds_read_b128 v[196:199], v147 offset:3072
	ds_read_b128 v[200:203], v147 offset:4096
	ds_read_b128 v[204:207], v147 offset:5120
	ds_read_b128 v[208:211], v147 offset:6144
	ds_read_b128 v[212:215], v147 offset:7168
	global_load_lds_dwordx4 v[172:173], off
	v_lshl_add_u64 v[172:173], v[140:141], 0, s[20:21]
	s_add_i32 m0, s27, 0xe000
	s_nop 0
	global_load_lds_dwordx4 v[172:173], off
	s_waitcnt lgkmcnt(8)
	s_barrier
	s_waitcnt lgkmcnt(0)
	s_waitcnt lgkmcnt(0)
	v_mfma_f32_16x16x32_bf16 v[126:129], v[148:151], v[164:167], 0
	v_mfma_f32_16x16x32_bf16 v[122:125], v[156:159], v[164:167], 0
	v_mfma_f32_16x16x32_bf16 v[118:121], v[148:151], v[192:195], 0
	v_mfma_f32_16x16x32_bf16 v[114:117], v[156:159], v[192:195], 0
	v_mfma_f32_16x16x32_bf16 v[102:105], v[148:151], v[200:203], 0
	v_mfma_f32_16x16x32_bf16 v[98:101], v[156:159], v[200:203], 0
	v_mfma_f32_16x16x32_bf16 v[86:89], v[148:151], v[208:211], 0
	v_mfma_f32_16x16x32_bf16 v[82:85], v[156:159], v[208:211], 0
	v_mfma_f32_16x16x32_bf16 v[126:129], v[152:155], v[168:171], v[126:129]
	v_mfma_f32_16x16x32_bf16 v[122:125], v[160:163], v[168:171], v[122:125]
	v_mfma_f32_16x16x32_bf16 v[118:121], v[152:155], v[196:199], v[118:121]
	v_mfma_f32_16x16x32_bf16 v[114:117], v[160:163], v[196:199], v[114:117]
	v_mfma_f32_16x16x32_bf16 v[102:105], v[152:155], v[204:207], v[102:105]
	v_mfma_f32_16x16x32_bf16 v[98:101], v[160:163], v[204:207], v[98:101]
	v_mfma_f32_16x16x32_bf16 v[86:89], v[152:155], v[212:215], v[86:89]
	v_mfma_f32_16x16x32_bf16 v[82:85], v[160:163], v[212:215], v[82:85]
	s_barrier
	s_add_i32 s59, 0, 0x14000
	v_add_u32_e32 v172, s59, v145
	s_add_i32 s56, s58, s26
	ds_read_b128 v[216:219], v172
	ds_read_b128 v[220:223], v172 offset:1024
	ds_read_b128 v[224:227], v172 offset:2048
	ds_read_b128 v[228:231], v172 offset:3072
	v_lshl_add_u64 v[172:173], s[22:23], 0, v[0:1]
	s_mov_b32 m0, s56
	v_lshl_add_u64 v[232:233], s[22:23], 0, v[130:131]
	global_load_lds_dwordx4 v[172:173], off
	s_add_i32 m0, s56, 0x2000
	s_nop 0
	global_load_lds_dwordx4 v[232:233], off
	s_barrier
	s_waitcnt lgkmcnt(0)
	s_waitcnt lgkmcnt(0)
	v_mfma_f32_16x16x32_bf16 v[110:113], v[216:219], v[164:167], 0
	v_mfma_f32_16x16x32_bf16 v[106:109], v[224:227], v[164:167], 0
	v_mfma_f32_16x16x32_bf16 v[94:97], v[216:219], v[192:195], 0
	v_mfma_f32_16x16x32_bf16 v[90:93], v[224:227], v[192:195], 0
	v_mfma_f32_16x16x32_bf16 v[78:81], v[216:219], v[200:203], 0
	v_mfma_f32_16x16x32_bf16 v[74:77], v[224:227], v[200:203], 0
	v_mfma_f32_16x16x32_bf16 v[70:73], v[216:219], v[208:211], 0
	v_mfma_f32_16x16x32_bf16 v[66:69], v[224:227], v[208:211], 0
	v_mfma_f32_16x16x32_bf16 v[110:113], v[220:223], v[168:171], v[110:113]
	v_mfma_f32_16x16x32_bf16 v[106:109], v[228:231], v[168:171], v[106:109]
	v_mfma_f32_16x16x32_bf16 v[94:97], v[220:223], v[196:199], v[94:97]
	v_mfma_f32_16x16x32_bf16 v[90:93], v[228:231], v[196:199], v[90:93]
	v_mfma_f32_16x16x32_bf16 v[78:81], v[220:223], v[204:207], v[78:81]
	v_mfma_f32_16x16x32_bf16 v[74:77], v[228:231], v[204:207], v[74:77]
	v_mfma_f32_16x16x32_bf16 v[70:73], v[220:223], v[212:215], v[70:73]
	v_mfma_f32_16x16x32_bf16 v[66:69], v[228:231], v[212:215], v[66:69]
	s_mov_b32 m0, s27
	v_lshl_add_u64 v[234:235], s[30:31], 0, v[134:135]
	s_barrier
	ds_read_b128 v[164:167], v147 offset:16384
	ds_read_b128 v[168:171], v147 offset:17408
	ds_read_b128 v[192:195], v147 offset:18432
	ds_read_b128 v[196:199], v147 offset:19456
	ds_read_b128 v[200:203], v147 offset:20480
	ds_read_b128 v[204:207], v147 offset:21504
	ds_read_b128 v[208:211], v147 offset:22528
	ds_read_b128 v[212:215], v147 offset:23552
	global_load_lds_dwordx4 v[234:235], off
	v_lshl_add_u64 v[234:235], s[30:31], 0, v[132:133]
	s_mov_b32 m0, s34
	s_nop 0
	global_load_lds_dwordx4 v[234:235], off
	s_barrier
; #define PG8_STAGE(bufoff, gbase, voff) do { _Pragma("unroll") for (int _i = 0; _i < 2; ++_i) \
;         __builtin_amdgcn_global_load_lds((const unsigned*)((const char*)(gbase) + (voff)[_i]), (LAS unsigned*)(lds + (bufoff) + ldsw + _i * 8192), 16, 0, 0); } while (0)
; #define PG8_LDA(dst, b, h) do { _Pragma("unroll") for (int m = 0; m < 4; ++m) _Pragma("unroll") for (int k = 0; k < 2; ++k) dst[m][k] = *(const LAS bf16x8*)(lds + PG8_SA(b, h) + aoff + m * 2048 + k * 1024); } while (0)
; #define PG8_LDB(dst, b, h) do { _Pragma("unroll") for (int n = 0; n < 2; ++n) _Pragma("unroll") for (int k = 0; k < 2; ++k) dst[n][k] = *(const LAS bf16x8*)(lds + PG8_SB(b, h) + boff + n * 2048 + k * 1024); } while (0)
; #define PG8_WAIT_V(n) asm volatile("s_waitcnt vmcnt(" #n ")" ::: "memory")
; #define PG8_WAIT_L(n) asm volatile("s_waitcnt lgkmcnt(" #n ")" ::: "memory")
; #define PG8_BAR __builtin_amdgcn_s_barrier()
; #define PG8_SCHED __builtin_amdgcn_sched_barrier(0)
; template <bool REMAP>
; DI void gemm_phase(LAS unsigned char* lds, const u16* A, int lda, const u16* Bt, int K, u16* O, int ldc, int nunits) {
;     ...
;             PG8_LDB(B0, 0, 0); PG8_SCHED; PG8_LDA(At, 0, 0); PG8_STAGE(PG8_SA(1, 1), a1 + hstepA, voffA);
;             PG8_WAIT_L(8); PG8_BAR; PG8_WAIT_L(0); PG8_MMA(0, 0, At, B0); PG8_BAR; PG8_SCHED;
;             PG8_LDB(B1, 0, 1); PG8_STAGE(PG8_SB(0, 0), b2, voffB);
;             PG8_BAR; PG8_WAIT_L(0); PG8_MMA(0, 1, At, B1); PG8_BAR;
;             PG8_LDA(At, 0, 1); PG8_STAGE(PG8_SA(0, 0), a2, voffA);
;             PG8_BAR; PG8_WAIT_L(0); PG8_MMA(1, 0, At, B0); PG8_BAR; PG8_SCHED;
;             PG8_STAGE(PG8_SB(0, 1), b2 + hstepB, voffB);
;             PG8_WAIT_V(6); PG8_BAR; PG8_MMA(1, 1, At, B1); PG8_BAR;
;             PG8_LDB(B0, 1, 0); PG8_SCHED; PG8_LDA(At, 1, 0); PG8_STAGE(PG8_SA(0, 1), a2 + hstepA, voffA);
;             PG8_WAIT_L(8); PG8_BAR; PG8_WAIT_L(0); PG8_MMA(0, 0, At, B0); PG8_BAR; PG8_SCHED;
;             PG8_LDB(B1, 1, 1); PG8_STAGE(PG8_SB(1, 0), b3, voffB);
;             PG8_BAR; PG8_WAIT_L(0); PG8_MMA(0, 1, At, B1); PG8_BAR;
;             PG8_LDA(At, 1, 1); PG8_STAGE(PG8_SA(1, 0), a3, voffA);
;             PG8_BAR; PG8_WAIT_L(0); PG8_MMA(1, 0, At, B0); PG8_BAR; PG8_SCHED;
;             PG8_STAGE(PG8_SB(1, 1), b3 + hstepB, voffB);
;             PG8_WAIT_V(6); PG8_BAR; PG8_MMA(1, 1, At, B1); PG8_BAR;
	s_waitcnt lgkmcnt(0)
	s_waitcnt lgkmcnt(0)
	v_mfma_f32_16x16x32_bf16 v[62:65], v[148:151], v[164:167], 0
	v_mfma_f32_16x16x32_bf16 v[58:61], v[156:159], v[164:167], 0
	v_mfma_f32_16x16x32_bf16 v[54:57], v[148:151], v[192:195], 0
	v_mfma_f32_16x16x32_bf16 v[50:53], v[156:159], v[192:195], 0
	v_mfma_f32_16x16x32_bf16 v[38:41], v[148:151], v[200:203], 0
	v_mfma_f32_16x16x32_bf16 v[34:37], v[156:159], v[200:203], 0
	v_mfma_f32_16x16x32_bf16 v[22:25], v[148:151], v[208:211], 0
	v_mfma_f32_16x16x32_bf16 v[18:21], v[156:159], v[208:211], 0
	v_mfma_f32_16x16x32_bf16 v[62:65], v[152:155], v[168:171], v[62:65]
	v_mfma_f32_16x16x32_bf16 v[58:61], v[160:163], v[168:171], v[58:61]
	v_mfma_f32_16x16x32_bf16 v[54:57], v[152:155], v[196:199], v[54:57]
	v_mfma_f32_16x16x32_bf16 v[50:53], v[160:163], v[196:199], v[50:53]
	v_mfma_f32_16x16x32_bf16 v[38:41], v[152:155], v[204:207], v[38:41]
	v_mfma_f32_16x16x32_bf16 v[34:37], v[160:163], v[204:207], v[34:37]
	v_mfma_f32_16x16x32_bf16 v[22:25], v[152:155], v[212:215], v[22:25]
	v_mfma_f32_16x16x32_bf16 v[18:21], v[160:163], v[212:215], v[18:21]
	s_barrier
	s_add_u32 s56, s22, 0x40000
	s_addc_u32 s57, s23, 0
	s_add_i32 s58, s59, s26
	v_lshl_add_u64 v[148:149], s[56:57], 0, v[0:1]
	s_mov_b32 m0, s58
	s_nop 0
	global_load_lds_dwordx4 v[148:149], off
	v_lshl_add_u64 v[148:149], s[56:57], 0, v[130:131]
	s_add_i32 m0, s58, 0x2000
	s_nop 0
	global_load_lds_dwordx4 v[148:149], off
	s_waitcnt vmcnt(6)
	s_barrier
	v_mfma_f32_16x16x32_bf16 v[46:49], v[216:219], v[164:167], 0
	v_mfma_f32_16x16x32_bf16 v[42:45], v[224:227], v[164:167], 0
	v_mfma_f32_16x16x32_bf16 v[30:33], v[216:219], v[192:195], 0
	v_mfma_f32_16x16x32_bf16 v[26:29], v[224:227], v[192:195], 0
	v_mfma_f32_16x16x32_bf16 v[14:17], v[216:219], v[200:203], 0
	v_mfma_f32_16x16x32_bf16 v[10:13], v[224:227], v[200:203], 0
	v_mfma_f32_16x16x32_bf16 v[6:9], v[216:219], v[208:211], 0
	v_mfma_f32_16x16x32_bf16 v[2:5], v[224:227], v[208:211], 0
	v_mfma_f32_16x16x32_bf16 v[46:49], v[220:223], v[168:171], v[46:49]
	v_mfma_f32_16x16x32_bf16 v[42:45], v[228:231], v[168:171], v[42:45]
	v_mfma_f32_16x16x32_bf16 v[30:33], v[220:223], v[196:199], v[30:33]
	v_mfma_f32_16x16x32_bf16 v[26:29], v[228:231], v[196:199], v[26:29]
	v_mfma_f32_16x16x32_bf16 v[14:17], v[220:223], v[204:207], v[14:17]
	v_mfma_f32_16x16x32_bf16 v[10:13], v[228:231], v[204:207], v[10:13]
	v_mfma_f32_16x16x32_bf16 v[6:9], v[220:223], v[212:215], v[6:9]
	v_mfma_f32_16x16x32_bf16 v[2:5], v[228:231], v[212:215], v[2:5]
	s_add_i32 s56, 0, 0x18000
	v_add_u32_e32 v160, s56, v145
	s_barrier
	ds_read_b128 v[148:151], v160
	ds_read_b128 v[152:155], v160 offset:1024
	ds_read_b128 v[156:159], v160 offset:2048
	ds_read_b128 v[160:163], v160 offset:3072
	s_add_u32 s30, s30, 0x40000
	s_addc_u32 s31, s31, 0
	s_mov_b32 m0, s35
	v_lshl_add_u64 v[216:217], s[30:31], 0, v[134:135]
	ds_read_b128 v[164:167], v147 offset:32768
	ds_read_b128 v[168:171], v147 offset:33792
	ds_read_b128 v[192:195], v147 offset:34816
	ds_read_b128 v[196:199], v147 offset:35840
	ds_read_b128 v[200:203], v147 offset:36864
	ds_read_b128 v[204:207], v147 offset:37888
	ds_read_b128 v[208:211], v147 offset:38912
	ds_read_b128 v[212:215], v147 offset:39936
	global_load_lds_dwordx4 v[216:217], off
	v_lshl_add_u64 v[216:217], s[30:31], 0, v[132:133]
	s_mov_b32 m0, s36
	s_nop 0
	global_load_lds_dwordx4 v[216:217], off
	s_waitcnt lgkmcnt(8)
	s_barrier
	s_waitcnt lgkmcnt(0)
	s_waitcnt lgkmcnt(0)
	v_mfma_f32_16x16x32_bf16 v[126:129], v[148:151], v[164:167], v[126:129]
	v_mfma_f32_16x16x32_bf16 v[122:125], v[156:159], v[164:167], v[122:125]
	v_mfma_f32_16x16x32_bf16 v[118:121], v[148:151], v[192:195], v[118:121]
	v_mfma_f32_16x16x32_bf16 v[114:117], v[156:159], v[192:195], v[114:117]
	v_mfma_f32_16x16x32_bf16 v[102:105], v[148:151], v[200:203], v[102:105]
	v_mfma_f32_16x16x32_bf16 v[98:101], v[156:159], v[200:203], v[98:101]
	v_mfma_f32_16x16x32_bf16 v[86:89], v[148:151], v[208:211], v[86:89]
	v_mfma_f32_16x16x32_bf16 v[82:85], v[156:159], v[208:211], v[82:85]
	v_mfma_f32_16x16x32_bf16 v[126:129], v[152:155], v[168:171], v[126:129]
	v_mfma_f32_16x16x32_bf16 v[122:125], v[160:163], v[168:171], v[122:125]
	v_mfma_f32_16x16x32_bf16 v[118:121], v[152:155], v[196:199], v[118:121]
	v_mfma_f32_16x16x32_bf16 v[114:117], v[160:163], v[196:199], v[114:117]
	v_mfma_f32_16x16x32_bf16 v[102:105], v[152:155], v[204:207], v[102:105]
	v_mfma_f32_16x16x32_bf16 v[98:101], v[160:163], v[204:207], v[98:101]
	v_mfma_f32_16x16x32_bf16 v[86:89], v[152:155], v[212:215], v[86:89]
	v_mfma_f32_16x16x32_bf16 v[82:85], v[160:163], v[212:215], v[82:85]
	s_barrier
	s_add_i32 s30, 0, 0x1c000
	s_add_i32 s31, s56, s26
	v_add_u32_e32 v228, s30, v145
	v_lshl_add_u64 v[172:173], v[172:173], 0, s[18:19]
	s_mov_b32 m0, s31
	ds_read_b128 v[216:219], v228
	ds_read_b128 v[220:223], v228 offset:1024
	ds_read_b128 v[224:227], v228 offset:2048
	ds_read_b128 v[228:231], v228 offset:3072
	global_load_lds_dwordx4 v[172:173], off
	v_lshl_add_u64 v[172:173], v[232:233], 0, s[18:19]
	s_add_i32 m0, s31, 0x2000
	s_nop 0
	global_load_lds_dwordx4 v[172:173], off
	s_barrier
; #define PG8_STAGE(bufoff, gbase, voff) do { _Pragma("unroll") for (int _i = 0; _i < 2; ++_i) \
;         __builtin_amdgcn_global_load_lds((const unsigned*)((const char*)(gbase) + (voff)[_i]), (LAS unsigned*)(lds + (bufoff) + ldsw + _i * 8192), 16, 0, 0); } while (0)
; #define PG8_LDA(dst, b, h) do { _Pragma("unroll") for (int m = 0; m < 4; ++m) _Pragma("unroll") for (int k = 0; k < 2; ++k) dst[m][k] = *(const LAS bf16x8*)(lds + PG8_SA(b, h) + aoff + m * 2048 + k * 1024); } while (0)
; #define PG8_LDB(dst, b, h) do { _Pragma("unroll") for (int n = 0; n < 2; ++n) _Pragma("unroll") for (int k = 0; k < 2; ++k) dst[n][k] = *(const LAS bf16x8*)(lds + PG8_SB(b, h) + boff + n * 2048 + k * 1024); } while (0)
; #define PG8_MMA(ai, bj, At, Bt_) do { __builtin_amdgcn_s_setprio(1); _Pragma("unroll") for (int m = 0; m < 4; ++m) _Pragma("unroll") for (int n = 0; n < 2; ++n) _Pragma("unroll") for (int k = 0; k < 2; ++k) \
;         acc[ai][bj][m][n] = __builtin_amdgcn_mfma_f32_16x16x32_bf16(Bt_[n][k], At[m][k], acc[ai][bj][m][n], 0, 0, 0); __builtin_amdgcn_s_setprio(0); } while (0)
; #define PG8_WAIT_V(n) asm volatile("s_waitcnt vmcnt(" #n ")" ::: "memory")
; #define PG8_WAIT_L(n) asm volatile("s_waitcnt lgkmcnt(" #n ")" ::: "memory")
; #define PG8_BAR __builtin_amdgcn_s_barrier()
; #define PG8_SCHED __builtin_amdgcn_sched_barrier(0)
; template <bool REMAP>
; DI void gemm_phase(LAS unsigned char* lds, const u16* A, int lda, const u16* Bt, int K, u16* O, int ldc, int nunits) {
;     ...
;             const char* a1 = cA + akb(t + 1);
;             const char* a2 = last ? nA + akb(0) : cA + akb(t + 2); const char* b2 = last ? nB : cB + (size_t)(t + 2) * kstep;
;             const char* a3 = last ? nA + akb(1) : cA + akb(t + 3); const char* b3 = b2 + kstep;
;     ...
;             PG8_LDB(B0, 1, 0); PG8_SCHED; PG8_LDA(At, 1, 0); PG8_STAGE(PG8_SA(0, 1), a2 + hstepA, voffA);
;             PG8_WAIT_L(8); PG8_BAR; PG8_WAIT_L(0); PG8_MMA(0, 0, At, B0); PG8_BAR; PG8_SCHED;
;             PG8_LDB(B1, 1, 1); PG8_STAGE(PG8_SB(1, 0), b3, voffB);
;             PG8_BAR; PG8_WAIT_L(0); PG8_MMA(0, 1, At, B1); PG8_BAR;
;             PG8_LDA(At, 1, 1); PG8_STAGE(PG8_SA(1, 0), a3, voffA);
;             PG8_BAR; PG8_WAIT_L(0); PG8_MMA(1, 0, At, B0); PG8_BAR; PG8_SCHED;
;             PG8_STAGE(PG8_SB(1, 1), b3 + hstepB, voffB);
;             PG8_WAIT_V(6); PG8_BAR; PG8_MMA(1, 1, At, B1); PG8_BAR;
	s_waitcnt lgkmcnt(0)
	s_waitcnt lgkmcnt(0)
	v_mfma_f32_16x16x32_bf16 v[110:113], v[216:219], v[164:167], v[110:113]
	v_mfma_f32_16x16x32_bf16 v[106:109], v[224:227], v[164:167], v[106:109]
	v_mfma_f32_16x16x32_bf16 v[94:97], v[216:219], v[192:195], v[94:97]
	v_mfma_f32_16x16x32_bf16 v[90:93], v[224:227], v[192:195], v[90:93]
	v_mfma_f32_16x16x32_bf16 v[78:81], v[216:219], v[200:203], v[78:81]
	v_mfma_f32_16x16x32_bf16 v[74:77], v[224:227], v[200:203], v[74:77]
	v_mfma_f32_16x16x32_bf16 v[70:73], v[216:219], v[208:211], v[70:73]
	v_mfma_f32_16x16x32_bf16 v[66:69], v[224:227], v[208:211], v[66:69]
	v_mfma_f32_16x16x32_bf16 v[110:113], v[220:223], v[168:171], v[110:113]
	v_mfma_f32_16x16x32_bf16 v[106:109], v[228:231], v[168:171], v[106:109]
	v_mfma_f32_16x16x32_bf16 v[94:97], v[220:223], v[196:199], v[94:97]
	v_mfma_f32_16x16x32_bf16 v[90:93], v[228:231], v[196:199], v[90:93]
	v_mfma_f32_16x16x32_bf16 v[78:81], v[220:223], v[204:207], v[78:81]
	v_mfma_f32_16x16x32_bf16 v[74:77], v[228:231], v[204:207], v[74:77]
	v_mfma_f32_16x16x32_bf16 v[70:73], v[220:223], v[212:215], v[70:73]
	v_mfma_f32_16x16x32_bf16 v[66:69], v[228:231], v[212:215], v[66:69]
	s_mov_b32 m0, s37
	v_lshl_add_u64 v[172:173], s[28:29], 0, v[134:135]
	s_barrier
	ds_read_b128 v[164:167], v147 offset:49152
	ds_read_b128 v[168:171], v147 offset:50176
	ds_read_b128 v[192:195], v147 offset:51200
	ds_read_b128 v[196:199], v147 offset:52224
	ds_read_b128 v[200:203], v147 offset:53248
	ds_read_b128 v[204:207], v147 offset:54272
	ds_read_b128 v[208:211], v147 offset:55296
	ds_read_b128 v[212:215], v147 offset:56320
	global_load_lds_dwordx4 v[172:173], off
	v_lshl_add_u64 v[172:173], s[28:29], 0, v[132:133]
	s_mov_b32 m0, s38
	s_nop 0
	global_load_lds_dwordx4 v[172:173], off
	s_barrier
	s_waitcnt lgkmcnt(0)
	s_waitcnt lgkmcnt(0)
	v_mfma_f32_16x16x32_bf16 v[62:65], v[148:151], v[164:167], v[62:65]
	v_mfma_f32_16x16x32_bf16 v[58:61], v[156:159], v[164:167], v[58:61]
	v_mfma_f32_16x16x32_bf16 v[54:57], v[148:151], v[192:195], v[54:57]
	v_mfma_f32_16x16x32_bf16 v[50:53], v[156:159], v[192:195], v[50:53]
	v_mfma_f32_16x16x32_bf16 v[38:41], v[148:151], v[200:203], v[38:41]
	v_mfma_f32_16x16x32_bf16 v[34:37], v[156:159], v[200:203], v[34:37]
	v_mfma_f32_16x16x32_bf16 v[22:25], v[148:151], v[208:211], v[22:25]
	v_mfma_f32_16x16x32_bf16 v[18:21], v[156:159], v[208:211], v[18:21]
	v_mfma_f32_16x16x32_bf16 v[62:65], v[152:155], v[168:171], v[62:65]
	v_mfma_f32_16x16x32_bf16 v[58:61], v[160:163], v[168:171], v[58:61]
	v_mfma_f32_16x16x32_bf16 v[54:57], v[152:155], v[196:199], v[54:57]
	v_mfma_f32_16x16x32_bf16 v[50:53], v[160:163], v[196:199], v[50:53]
	v_mfma_f32_16x16x32_bf16 v[38:41], v[152:155], v[204:207], v[38:41]
	v_mfma_f32_16x16x32_bf16 v[34:37], v[160:163], v[204:207], v[34:37]
	v_mfma_f32_16x16x32_bf16 v[22:25], v[152:155], v[212:215], v[22:25]
	v_mfma_f32_16x16x32_bf16 v[18:21], v[160:163], v[212:215], v[18:21]
	s_barrier
	s_add_u32 s22, s22, 0x40080
	s_addc_u32 s23, s23, 0
	s_add_i32 s28, s30, s26
	v_lshl_add_u64 v[148:149], s[22:23], 0, v[0:1]
	s_mov_b32 m0, s28
	s_nop 0
	global_load_lds_dwordx4 v[148:149], off
	v_lshl_add_u64 v[148:149], s[22:23], 0, v[130:131]
	s_add_i32 m0, s28, 0x2000
	s_nop 0
	global_load_lds_dwordx4 v[148:149], off
	s_waitcnt vmcnt(6)
	s_barrier
	v_mfma_f32_16x16x32_bf16 v[46:49], v[216:219], v[164:167], v[46:49]
	v_mfma_f32_16x16x32_bf16 v[42:45], v[224:227], v[164:167], v[42:45]
	v_mfma_f32_16x16x32_bf16 v[30:33], v[216:219], v[192:195], v[30:33]
	v_mfma_f32_16x16x32_bf16 v[26:29], v[224:227], v[192:195], v[26:29]
	v_mfma_f32_16x16x32_bf16 v[14:17], v[216:219], v[200:203], v[14:17]
	v_mfma_f32_16x16x32_bf16 v[10:13], v[224:227], v[200:203], v[10:13]
	v_mfma_f32_16x16x32_bf16 v[6:9], v[216:219], v[208:211], v[6:9]
	v_mfma_f32_16x16x32_bf16 v[2:5], v[224:227], v[208:211], v[2:5]
	v_mfma_f32_16x16x32_bf16 v[46:49], v[220:223], v[168:171], v[46:49]
	v_mfma_f32_16x16x32_bf16 v[42:45], v[228:231], v[168:171], v[42:45]
	v_mfma_f32_16x16x32_bf16 v[30:33], v[220:223], v[196:199], v[30:33]
	v_mfma_f32_16x16x32_bf16 v[26:29], v[228:231], v[196:199], v[26:29]
	v_mfma_f32_16x16x32_bf16 v[14:17], v[220:223], v[204:207], v[14:17]
	v_mfma_f32_16x16x32_bf16 v[10:13], v[228:231], v[204:207], v[10:13]
	v_mfma_f32_16x16x32_bf16 v[6:9], v[220:223], v[212:215], v[6:9]
	v_mfma_f32_16x16x32_bf16 v[2:5], v[228:231], v[212:215], v[2:5]
	s_add_i32 s55, s55, 2
	s_add_u32 s20, s20, 0x100
	s_addc_u32 s21, s21, 0
	s_add_u32 s22, s10, s20
	s_addc_u32 s23, s11, s21
	s_add_u32 s30, s22, 0x100
	s_addc_u32 s31, s23, 0
	s_add_u32 s56, s51, s20
	s_addc_u32 s57, s54, s21
	s_add_u32 s22, s22, 0x180
	s_addc_u32 s23, s23, 0
	s_add_i32 s58, 0, 0x10000
	v_add_u32_e32 v160, s58, v145
	s_cmp_gt_u32 s55, 13
	s_barrier
; #define PG8_STAGE(bufoff, gbase, voff) do { _Pragma("unroll") for (int _i = 0; _i < 2; ++_i) \
;         __builtin_amdgcn_global_load_lds((const unsigned*)((const char*)(gbase) + (voff)[_i]), (LAS unsigned*)(lds + (bufoff) + ldsw + _i * 8192), 16, 0, 0); } while (0)
; #define PG8_LDA(dst, b, h) do { _Pragma("unroll") for (int m = 0; m < 4; ++m) _Pragma("unroll") for (int k = 0; k < 2; ++k) dst[m][k] = *(const LAS bf16x8*)(lds + PG8_SA(b, h) + aoff + m * 2048 + k * 1024); } while (0)
; #define PG8_LDB(dst, b, h) do { _Pragma("unroll") for (int n = 0; n < 2; ++n) _Pragma("unroll") for (int k = 0; k < 2; ++k) dst[n][k] = *(const LAS bf16x8*)(lds + PG8_SB(b, h) + boff + n * 2048 + k * 1024); } while (0)
; #define PG8_MMA(ai, bj, At, Bt_) do { __builtin_amdgcn_s_setprio(1); _Pragma("unroll") for (int m = 0; m < 4; ++m) _Pragma("unroll") for (int n = 0; n < 2; ++n) _Pragma("unroll") for (int k = 0; k < 2; ++k) \
;         acc[ai][bj][m][n] = __builtin_amdgcn_mfma_f32_16x16x32_bf16(Bt_[n][k], At[m][k], acc[ai][bj][m][n], 0, 0, 0); __builtin_amdgcn_s_setprio(0); } while (0)
; #define PG8_WAIT_V(n) asm volatile("s_waitcnt vmcnt(" #n ")" ::: "memory")
; #define PG8_WAIT_L(n) asm volatile("s_waitcnt lgkmcnt(" #n ")" ::: "memory")
; #define PG8_BAR __builtin_amdgcn_s_barrier()
; template <bool REMAP>
; DI void gemm_phase(LAS unsigned char* lds, const u16* A, int lda, const u16* Bt, int K, u16* O, int ldc, int nunits) {
;     ...
;             const bool last = (t == nt - 2);
;             const char* a1 = cA + akb(t + 1);
;             const char* a2 = last ? nA + akb(0) : cA + akb(t + 2); const char* b2 = last ? nB : cB + (size_t)(t + 2) * kstep;
;             const char* a3 = last ? nA + akb(1) : cA + akb(t + 3); const char* b3 = b2 + kstep;
;             PG8_LDB(B0, 0, 0); PG8_SCHED; PG8_LDA(At, 0, 0); PG8_STAGE(PG8_SA(1, 1), a1 + hstepA, voffA);
;             PG8_WAIT_L(8); PG8_BAR; PG8_WAIT_L(0); PG8_MMA(0, 0, At, B0); PG8_BAR; PG8_SCHED;
;             PG8_LDB(B1, 0, 1); PG8_STAGE(PG8_SB(0, 0), b2, voffB);
;             PG8_BAR; PG8_WAIT_L(0); PG8_MMA(0, 1, At, B1); PG8_BAR;
;             PG8_LDA(At, 0, 1); PG8_STAGE(PG8_SA(0, 0), a2, voffA);
;             PG8_BAR; PG8_WAIT_L(0); PG8_MMA(1, 0, At, B0); PG8_BAR; PG8_SCHED;
;             PG8_STAGE(PG8_SB(0, 1), b2 + hstepB, voffB);
;             PG8_WAIT_V(6); PG8_BAR; PG8_MMA(1, 1, At, B1); PG8_BAR;
.LBB0_137:
	ds_read_b128 v[148:151], v160
	ds_read_b128 v[152:155], v160 offset:1024
	ds_read_b128 v[156:159], v160 offset:2048
	ds_read_b128 v[160:163], v160 offset:3072
	s_cmpk_eq_i32 s20, 0x700
	s_cselect_b32 s29, s50, s23
	s_cselect_b32 s28, s49, s22
	s_cselect_b32 s23, s7, s57
	s_cselect_b32 s22, s47, s56
	s_cselect_b32 s31, s5, s31
	s_cselect_b32 s30, s46, s30
	v_lshl_add_u64 v[172:173], v[142:143], 0, s[20:21]
	s_add_i32 m0, s27, 0xc000
	ds_read_b128 v[164:167], v147
	ds_read_b128 v[168:171], v147 offset:1024
	ds_read_b128 v[192:195], v147 offset:2048
	ds_read_b128 v[196:199], v147 offset:3072
	ds_read_b128 v[200:203], v147 offset:4096
	ds_read_b128 v[204:207], v147 offset:5120
	ds_read_b128 v[208:211], v147 offset:6144
	ds_read_b128 v[212:215], v147 offset:7168
	global_load_lds_dwordx4 v[172:173], off
	v_lshl_add_u64 v[172:173], v[140:141], 0, s[20:21]
	s_add_i32 m0, s27, 0xe000
	s_nop 0
	global_load_lds_dwordx4 v[172:173], off
	s_waitcnt lgkmcnt(8)
	s_barrier
	s_waitcnt lgkmcnt(0)
	s_waitcnt lgkmcnt(0)
	v_mfma_f32_16x16x32_bf16 v[126:129], v[148:151], v[164:167], v[126:129]
	v_mfma_f32_16x16x32_bf16 v[122:125], v[156:159], v[164:167], v[122:125]
	v_mfma_f32_16x16x32_bf16 v[118:121], v[148:151], v[192:195], v[118:121]
	v_mfma_f32_16x16x32_bf16 v[114:117], v[156:159], v[192:195], v[114:117]
	v_mfma_f32_16x16x32_bf16 v[102:105], v[148:151], v[200:203], v[102:105]
	v_mfma_f32_16x16x32_bf16 v[98:101], v[156:159], v[200:203], v[98:101]
	v_mfma_f32_16x16x32_bf16 v[86:89], v[148:151], v[208:211], v[86:89]
	v_mfma_f32_16x16x32_bf16 v[82:85], v[156:159], v[208:211], v[82:85]
	v_mfma_f32_16x16x32_bf16 v[126:129], v[152:155], v[168:171], v[126:129]
	v_mfma_f32_16x16x32_bf16 v[122:125], v[160:163], v[168:171], v[122:125]
	v_mfma_f32_16x16x32_bf16 v[118:121], v[152:155], v[196:199], v[118:121]
	v_mfma_f32_16x16x32_bf16 v[114:117], v[160:163], v[196:199], v[114:117]
	v_mfma_f32_16x16x32_bf16 v[102:105], v[152:155], v[204:207], v[102:105]
	v_mfma_f32_16x16x32_bf16 v[98:101], v[160:163], v[204:207], v[98:101]
	v_mfma_f32_16x16x32_bf16 v[86:89], v[152:155], v[212:215], v[86:89]
	v_mfma_f32_16x16x32_bf16 v[82:85], v[160:163], v[212:215], v[82:85]
	s_barrier
	s_add_i32 s59, 0, 0x14000
	v_add_u32_e32 v172, s59, v145
	s_add_i32 s56, s58, s26
	ds_read_b128 v[216:219], v172
	ds_read_b128 v[220:223], v172 offset:1024
	ds_read_b128 v[224:227], v172 offset:2048
	ds_read_b128 v[228:231], v172 offset:3072
	v_lshl_add_u64 v[172:173], s[22:23], 0, v[0:1]
	s_mov_b32 m0, s56
	v_lshl_add_u64 v[232:233], s[22:23], 0, v[130:131]
	global_load_lds_dwordx4 v[172:173], off
	s_add_i32 m0, s56, 0x2000
	s_nop 0
	global_load_lds_dwordx4 v[232:233], off
	s_barrier
	s_waitcnt lgkmcnt(0)
	s_waitcnt lgkmcnt(0)
	v_mfma_f32_16x16x32_bf16 v[110:113], v[216:219], v[164:167], v[110:113]
	v_mfma_f32_16x16x32_bf16 v[106:109], v[224:227], v[164:167], v[106:109]
	v_mfma_f32_16x16x32_bf16 v[94:97], v[216:219], v[192:195], v[94:97]
	v_mfma_f32_16x16x32_bf16 v[90:93], v[224:227], v[192:195], v[90:93]
	v_mfma_f32_16x16x32_bf16 v[78:81], v[216:219], v[200:203], v[78:81]
	v_mfma_f32_16x16x32_bf16 v[74:77], v[224:227], v[200:203], v[74:77]
	v_mfma_f32_16x16x32_bf16 v[70:73], v[216:219], v[208:211], v[70:73]
	v_mfma_f32_16x16x32_bf16 v[66:69], v[224:227], v[208:211], v[66:69]
	v_mfma_f32_16x16x32_bf16 v[110:113], v[220:223], v[168:171], v[110:113]
	v_mfma_f32_16x16x32_bf16 v[106:109], v[228:231], v[168:171], v[106:109]
	v_mfma_f32_16x16x32_bf16 v[94:97], v[220:223], v[196:199], v[94:97]
	v_mfma_f32_16x16x32_bf16 v[90:93], v[228:231], v[196:199], v[90:93]
	v_mfma_f32_16x16x32_bf16 v[78:81], v[220:223], v[204:207], v[78:81]
	v_mfma_f32_16x16x32_bf16 v[74:77], v[228:231], v[204:207], v[74:77]
	v_mfma_f32_16x16x32_bf16 v[70:73], v[220:223], v[212:215], v[70:73]
	v_mfma_f32_16x16x32_bf16 v[66:69], v[228:231], v[212:215], v[66:69]
	s_mov_b32 m0, s27
	v_lshl_add_u64 v[234:235], s[30:31], 0, v[134:135]
	s_barrier
	ds_read_b128 v[164:167], v147 offset:16384
	ds_read_b128 v[168:171], v147 offset:17408
	ds_read_b128 v[192:195], v147 offset:18432
	ds_read_b128 v[196:199], v147 offset:19456
	ds_read_b128 v[200:203], v147 offset:20480
	ds_read_b128 v[204:207], v147 offset:21504
	ds_read_b128 v[208:211], v147 offset:22528
	ds_read_b128 v[212:215], v147 offset:23552
	global_load_lds_dwordx4 v[234:235], off
	v_lshl_add_u64 v[234:235], s[30:31], 0, v[132:133]
	s_mov_b32 m0, s34
	s_nop 0
	global_load_lds_dwordx4 v[234:235], off
	s_barrier
	s_waitcnt lgkmcnt(0)
	s_waitcnt lgkmcnt(0)
	v_mfma_f32_16x16x32_bf16 v[62:65], v[148:151], v[164:167], v[62:65]
	v_mfma_f32_16x16x32_bf16 v[58:61], v[156:159], v[164:167], v[58:61]
	v_mfma_f32_16x16x32_bf16 v[54:57], v[148:151], v[192:195], v[54:57]
	v_mfma_f32_16x16x32_bf16 v[50:53], v[156:159], v[192:195], v[50:53]
	v_mfma_f32_16x16x32_bf16 v[38:41], v[148:151], v[200:203], v[38:41]
	v_mfma_f32_16x16x32_bf16 v[34:37], v[156:159], v[200:203], v[34:37]
	v_mfma_f32_16x16x32_bf16 v[22:25], v[148:151], v[208:211], v[22:25]
	v_mfma_f32_16x16x32_bf16 v[18:21], v[156:159], v[208:211], v[18:21]
	v_mfma_f32_16x16x32_bf16 v[62:65], v[152:155], v[168:171], v[62:65]
	v_mfma_f32_16x16x32_bf16 v[58:61], v[160:163], v[168:171], v[58:61]
	v_mfma_f32_16x16x32_bf16 v[54:57], v[152:155], v[196:199], v[54:57]
	v_mfma_f32_16x16x32_bf16 v[50:53], v[160:163], v[196:199], v[50:53]
	v_mfma_f32_16x16x32_bf16 v[38:41], v[152:155], v[204:207], v[38:41]
	v_mfma_f32_16x16x32_bf16 v[34:37], v[160:163], v[204:207], v[34:37]
	v_mfma_f32_16x16x32_bf16 v[22:25], v[152:155], v[212:215], v[22:25]
	v_mfma_f32_16x16x32_bf16 v[18:21], v[160:163], v[212:215], v[18:21]
	s_barrier
; #define PG8_STAGE(bufoff, gbase, voff) do { _Pragma("unroll") for (int _i = 0; _i < 2; ++_i) \
;         __builtin_amdgcn_global_load_lds((const unsigned*)((const char*)(gbase) + (voff)[_i]), (LAS unsigned*)(lds + (bufoff) + ldsw + _i * 8192), 16, 0, 0); } while (0)
; #define PG8_LDA(dst, b, h) do { _Pragma("unroll") for (int m = 0; m < 4; ++m) _Pragma("unroll") for (int k = 0; k < 2; ++k) dst[m][k] = *(const LAS bf16x8*)(lds + PG8_SA(b, h) + aoff + m * 2048 + k * 1024); } while (0)
; #define PG8_LDB(dst, b, h) do { _Pragma("unroll") for (int n = 0; n < 2; ++n) _Pragma("unroll") for (int k = 0; k < 2; ++k) dst[n][k] = *(const LAS bf16x8*)(lds + PG8_SB(b, h) + boff + n * 2048 + k * 1024); } while (0)
; #define PG8_MMA(ai, bj, At, Bt_) do { __builtin_amdgcn_s_setprio(1); _Pragma("unroll") for (int m = 0; m < 4; ++m) _Pragma("unroll") for (int n = 0; n < 2; ++n) _Pragma("unroll") for (int k = 0; k < 2; ++k) \
;         acc[ai][bj][m][n] = __builtin_amdgcn_mfma_f32_16x16x32_bf16(Bt_[n][k], At[m][k], acc[ai][bj][m][n], 0, 0, 0); __builtin_amdgcn_s_setprio(0); } while (0)
; #define PG8_WAIT_V(n) asm volatile("s_waitcnt vmcnt(" #n ")" ::: "memory")
; #define PG8_WAIT_L(n) asm volatile("s_waitcnt lgkmcnt(" #n ")" ::: "memory")
; #define PG8_BAR __builtin_amdgcn_s_barrier()
; #define PG8_SCHED __builtin_amdgcn_sched_barrier(0)
; template <bool REMAP>
; DI void gemm_phase(LAS unsigned char* lds, const u16* A, int lda, const u16* Bt, int K, u16* O, int ldc, int nunits) {
;     ...
;             PG8_LDA(At, 0, 1); PG8_STAGE(PG8_SA(0, 0), a2, voffA);
;             PG8_BAR; PG8_WAIT_L(0); PG8_MMA(1, 0, At, B0); PG8_BAR; PG8_SCHED;
;             PG8_STAGE(PG8_SB(0, 1), b2 + hstepB, voffB);
;             PG8_WAIT_V(6); PG8_BAR; PG8_MMA(1, 1, At, B1); PG8_BAR;
;             PG8_LDB(B0, 1, 0); PG8_SCHED; PG8_LDA(At, 1, 0); PG8_STAGE(PG8_SA(0, 1), a2 + hstepA, voffA);
;             PG8_WAIT_L(8); PG8_BAR; PG8_WAIT_L(0); PG8_MMA(0, 0, At, B0); PG8_BAR; PG8_SCHED;
;             PG8_LDB(B1, 1, 1); PG8_STAGE(PG8_SB(1, 0), b3, voffB);
;             PG8_BAR; PG8_WAIT_L(0); PG8_MMA(0, 1, At, B1); PG8_BAR;
;             PG8_LDA(At, 1, 1); PG8_STAGE(PG8_SA(1, 0), a3, voffA);
	s_add_u32 s56, s22, 0x40000
	s_addc_u32 s57, s23, 0
	s_add_i32 s58, s59, s26
	v_lshl_add_u64 v[148:149], s[56:57], 0, v[0:1]
	s_mov_b32 m0, s58
	s_nop 0
	global_load_lds_dwordx4 v[148:149], off
	v_lshl_add_u64 v[148:149], s[56:57], 0, v[130:131]
	s_add_i32 m0, s58, 0x2000
	s_nop 0
	global_load_lds_dwordx4 v[148:149], off
	s_waitcnt vmcnt(6)
	s_barrier
	v_mfma_f32_16x16x32_bf16 v[46:49], v[216:219], v[164:167], v[46:49]
	v_mfma_f32_16x16x32_bf16 v[42:45], v[224:227], v[164:167], v[42:45]
	v_mfma_f32_16x16x32_bf16 v[30:33], v[216:219], v[192:195], v[30:33]
	v_mfma_f32_16x16x32_bf16 v[26:29], v[224:227], v[192:195], v[26:29]
	v_mfma_f32_16x16x32_bf16 v[14:17], v[216:219], v[200:203], v[14:17]
	v_mfma_f32_16x16x32_bf16 v[10:13], v[224:227], v[200:203], v[10:13]
	v_mfma_f32_16x16x32_bf16 v[6:9], v[216:219], v[208:211], v[6:9]
	v_mfma_f32_16x16x32_bf16 v[2:5], v[224:227], v[208:211], v[2:5]
	v_mfma_f32_16x16x32_bf16 v[46:49], v[220:223], v[168:171], v[46:49]
	v_mfma_f32_16x16x32_bf16 v[42:45], v[228:231], v[168:171], v[42:45]
	v_mfma_f32_16x16x32_bf16 v[30:33], v[220:223], v[196:199], v[30:33]
	v_mfma_f32_16x16x32_bf16 v[26:29], v[228:231], v[196:199], v[26:29]
	v_mfma_f32_16x16x32_bf16 v[14:17], v[220:223], v[204:207], v[14:17]
	v_mfma_f32_16x16x32_bf16 v[10:13], v[228:231], v[204:207], v[10:13]
	v_mfma_f32_16x16x32_bf16 v[6:9], v[220:223], v[212:215], v[6:9]
	v_mfma_f32_16x16x32_bf16 v[2:5], v[228:231], v[212:215], v[2:5]
	s_add_i32 s56, 0, 0x18000
	v_add_u32_e32 v160, s56, v145
	s_barrier
	ds_read_b128 v[148:151], v160
	ds_read_b128 v[152:155], v160 offset:1024
	ds_read_b128 v[156:159], v160 offset:2048
	ds_read_b128 v[160:163], v160 offset:3072
	s_add_u32 s30, s30, 0x40000
	s_addc_u32 s31, s31, 0
	s_mov_b32 m0, s35
	v_lshl_add_u64 v[216:217], s[30:31], 0, v[134:135]
	ds_read_b128 v[164:167], v147 offset:32768
	ds_read_b128 v[168:171], v147 offset:33792
	ds_read_b128 v[192:195], v147 offset:34816
	ds_read_b128 v[196:199], v147 offset:35840
	ds_read_b128 v[200:203], v147 offset:36864
	ds_read_b128 v[204:207], v147 offset:37888
	ds_read_b128 v[208:211], v147 offset:38912
	ds_read_b128 v[212:215], v147 offset:39936
	global_load_lds_dwordx4 v[216:217], off
	v_lshl_add_u64 v[216:217], s[30:31], 0, v[132:133]
	s_mov_b32 m0, s36
	s_nop 0
	global_load_lds_dwordx4 v[216:217], off
	s_waitcnt lgkmcnt(8)
	s_barrier
	s_waitcnt lgkmcnt(0)
	s_waitcnt lgkmcnt(0)
	v_mfma_f32_16x16x32_bf16 v[126:129], v[148:151], v[164:167], v[126:129]
	v_mfma_f32_16x16x32_bf16 v[122:125], v[156:159], v[164:167], v[122:125]
	v_mfma_f32_16x16x32_bf16 v[118:121], v[148:151], v[192:195], v[118:121]
	v_mfma_f32_16x16x32_bf16 v[114:117], v[156:159], v[192:195], v[114:117]
	v_mfma_f32_16x16x32_bf16 v[102:105], v[148:151], v[200:203], v[102:105]
	v_mfma_f32_16x16x32_bf16 v[98:101], v[156:159], v[200:203], v[98:101]
	v_mfma_f32_16x16x32_bf16 v[86:89], v[148:151], v[208:211], v[86:89]
	v_mfma_f32_16x16x32_bf16 v[82:85], v[156:159], v[208:211], v[82:85]
	v_mfma_f32_16x16x32_bf16 v[126:129], v[152:155], v[168:171], v[126:129]
	v_mfma_f32_16x16x32_bf16 v[122:125], v[160:163], v[168:171], v[122:125]
	v_mfma_f32_16x16x32_bf16 v[118:121], v[152:155], v[196:199], v[118:121]
	v_mfma_f32_16x16x32_bf16 v[114:117], v[160:163], v[196:199], v[114:117]
	v_mfma_f32_16x16x32_bf16 v[102:105], v[152:155], v[204:207], v[102:105]
	v_mfma_f32_16x16x32_bf16 v[98:101], v[160:163], v[204:207], v[98:101]
	v_mfma_f32_16x16x32_bf16 v[86:89], v[152:155], v[212:215], v[86:89]
	v_mfma_f32_16x16x32_bf16 v[82:85], v[160:163], v[212:215], v[82:85]
	s_barrier
	s_add_i32 s30, 0, 0x1c000
	s_add_i32 s31, s56, s26
	v_add_u32_e32 v228, s30, v145
	v_lshl_add_u64 v[172:173], v[172:173], 0, s[18:19]
	s_mov_b32 m0, s31
	ds_read_b128 v[216:219], v228
	ds_read_b128 v[220:223], v228 offset:1024
	ds_read_b128 v[224:227], v228 offset:2048
	ds_read_b128 v[228:231], v228 offset:3072
	global_load_lds_dwordx4 v[172:173], off
	v_lshl_add_u64 v[172:173], v[232:233], 0, s[18:19]
	s_add_i32 m0, s31, 0x2000
	s_nop 0
	global_load_lds_dwordx4 v[172:173], off
	s_barrier
	s_waitcnt lgkmcnt(0)
	s_waitcnt lgkmcnt(0)
	v_mfma_f32_16x16x32_bf16 v[110:113], v[216:219], v[164:167], v[110:113]
	v_mfma_f32_16x16x32_bf16 v[106:109], v[224:227], v[164:167], v[106:109]
	v_mfma_f32_16x16x32_bf16 v[94:97], v[216:219], v[192:195], v[94:97]
	v_mfma_f32_16x16x32_bf16 v[90:93], v[224:227], v[192:195], v[90:93]
	v_mfma_f32_16x16x32_bf16 v[78:81], v[216:219], v[200:203], v[78:81]
	v_mfma_f32_16x16x32_bf16 v[74:77], v[224:227], v[200:203], v[74:77]
	v_mfma_f32_16x16x32_bf16 v[70:73], v[216:219], v[208:211], v[70:73]
	v_mfma_f32_16x16x32_bf16 v[66:69], v[224:227], v[208:211], v[66:69]
	v_mfma_f32_16x16x32_bf16 v[110:113], v[220:223], v[168:171], v[110:113]
	v_mfma_f32_16x16x32_bf16 v[106:109], v[228:231], v[168:171], v[106:109]
	v_mfma_f32_16x16x32_bf16 v[94:97], v[220:223], v[196:199], v[94:97]
	v_mfma_f32_16x16x32_bf16 v[90:93], v[228:231], v[196:199], v[90:93]
	v_mfma_f32_16x16x32_bf16 v[78:81], v[220:223], v[204:207], v[78:81]
	v_mfma_f32_16x16x32_bf16 v[74:77], v[228:231], v[204:207], v[74:77]
	v_mfma_f32_16x16x32_bf16 v[70:73], v[220:223], v[212:215], v[70:73]
	v_mfma_f32_16x16x32_bf16 v[66:69], v[228:231], v[212:215], v[66:69]
	s_mov_b32 m0, s37
	v_lshl_add_u64 v[172:173], s[28:29], 0, v[134:135]
	s_barrier
	ds_read_b128 v[164:167], v147 offset:49152
	ds_read_b128 v[168:171], v147 offset:50176
	ds_read_b128 v[192:195], v147 offset:51200
	ds_read_b128 v[196:199], v147 offset:52224
	ds_read_b128 v[200:203], v147 offset:53248
	ds_read_b128 v[204:207], v147 offset:54272
	ds_read_b128 v[208:211], v147 offset:55296
	ds_read_b128 v[212:215], v147 offset:56320
	global_load_lds_dwordx4 v[172:173], off
	v_lshl_add_u64 v[172:173], s[28:29], 0, v[132:133]
	s_mov_b32 m0, s38
	s_nop 0
	global_load_lds_dwordx4 v[172:173], off
	s_barrier
; DI unsigned pk2(float lo, float hi) { fl2_t f = {lo, hi}; bf2_t b = __builtin_convertvector(f, bf2_t); return __builtin_bit_cast(unsigned, b); }
; #define PG8_STAGE(bufoff, gbase, voff) do { _Pragma("unroll") for (int _i = 0; _i < 2; ++_i) \
;         __builtin_amdgcn_global_load_lds((const unsigned*)((const char*)(gbase) + (voff)[_i]), (LAS unsigned*)(lds + (bufoff) + ldsw + _i * 8192), 16, 0, 0); } while (0)
; #define PG8_MMA(ai, bj, At, Bt_) do { __builtin_amdgcn_s_setprio(1); _Pragma("unroll") for (int m = 0; m < 4; ++m) _Pragma("unroll") for (int n = 0; n < 2; ++n) _Pragma("unroll") for (int k = 0; k < 2; ++k) \
;         acc[ai][bj][m][n] = __builtin_amdgcn_mfma_f32_16x16x32_bf16(Bt_[n][k], At[m][k], acc[ai][bj][m][n], 0, 0, 0); __builtin_amdgcn_s_setprio(0); } while (0)
; #define PG8_WAIT_V(n) asm volatile("s_waitcnt vmcnt(" #n ")" ::: "memory")
; #define PG8_WAIT_L(n) asm volatile("s_waitcnt lgkmcnt(" #n ")" ::: "memory")
; #define PG8_BAR __builtin_amdgcn_s_barrier()
; #define PG8_SCHED __builtin_amdgcn_sched_barrier(0)
; template <bool REMAP>
; DI void gemm_phase(LAS unsigned char* lds, const u16* A, int lda, const u16* Bt, int K, u16* O, int ldc, int nunits) {
;     ...
;             const bool last = (t == nt - 2);
;             const char* a1 = cA + akb(t + 1);
;             const char* a2 = last ? nA + akb(0) : cA + akb(t + 2); const char* b2 = last ? nB : cB + (size_t)(t + 2) * kstep;
;             const char* a3 = last ? nA + akb(1) : cA + akb(t + 3); const char* b3 = b2 + kstep;
;     ...
;             PG8_BAR; PG8_WAIT_L(0); PG8_MMA(1, 0, At, B0); PG8_BAR; PG8_SCHED;
;             PG8_STAGE(PG8_SB(1, 1), b3 + hstepB, voffB);
;             PG8_WAIT_V(6); PG8_BAR; PG8_MMA(1, 1, At, B1); PG8_BAR;
;         }
;         {
;             const int row0 = cur.pm * BM + wr * 64 + fr, col0 = cur.pn * BM + wc * 32 + 8 * fq;
; #pragma unroll
;             for (int ai = 0; ai < 2; ++ai)
; #pragma unroll
;                 for (int m = 0; m < 4; ++m) { u16* rowp = O + (size_t)(row0 + ai * HALF + m * 16) * ldc + col0;
; #pragma unroll
;                     for (int bj = 0; bj < 2; ++bj) { const f32x4 v0 = acc[ai][bj][m][0], v1 = acc[ai][bj][m][1];
;                         u32x4 w = {pk2(v0[0], v0[1]), pk2(v0[2], v0[3]), pk2(v1[0], v1[1]), pk2(v1[2], v1[3])};
;                         *(u32x4*)(rowp + bj * HALF) = w; } }
;         }
	s_waitcnt lgkmcnt(0)
	s_waitcnt lgkmcnt(0)
	v_mfma_f32_16x16x32_bf16 v[62:65], v[148:151], v[164:167], v[62:65]
	v_mfma_f32_16x16x32_bf16 v[58:61], v[156:159], v[164:167], v[58:61]
	v_mfma_f32_16x16x32_bf16 v[54:57], v[148:151], v[192:195], v[54:57]
	v_mfma_f32_16x16x32_bf16 v[50:53], v[156:159], v[192:195], v[50:53]
	v_mfma_f32_16x16x32_bf16 v[38:41], v[148:151], v[200:203], v[38:41]
	v_mfma_f32_16x16x32_bf16 v[34:37], v[156:159], v[200:203], v[34:37]
	v_mfma_f32_16x16x32_bf16 v[22:25], v[148:151], v[208:211], v[22:25]
	v_mfma_f32_16x16x32_bf16 v[18:21], v[156:159], v[208:211], v[18:21]
	v_mfma_f32_16x16x32_bf16 v[62:65], v[152:155], v[168:171], v[62:65]
	v_mfma_f32_16x16x32_bf16 v[58:61], v[160:163], v[168:171], v[58:61]
	v_mfma_f32_16x16x32_bf16 v[54:57], v[152:155], v[196:199], v[54:57]
	v_mfma_f32_16x16x32_bf16 v[50:53], v[160:163], v[196:199], v[50:53]
	v_mfma_f32_16x16x32_bf16 v[38:41], v[152:155], v[204:207], v[38:41]
	v_mfma_f32_16x16x32_bf16 v[34:37], v[160:163], v[204:207], v[34:37]
	v_mfma_f32_16x16x32_bf16 v[22:25], v[152:155], v[212:215], v[22:25]
	v_mfma_f32_16x16x32_bf16 v[18:21], v[160:163], v[212:215], v[18:21]
	s_barrier
	s_add_u32 s22, s22, 0x40080
	s_addc_u32 s23, s23, 0
	s_add_i32 s28, s30, s26
	v_lshl_add_u64 v[148:149], s[22:23], 0, v[0:1]
	s_mov_b32 m0, s28
	s_nop 0
	global_load_lds_dwordx4 v[148:149], off
	v_lshl_add_u64 v[148:149], s[22:23], 0, v[130:131]
	s_add_i32 m0, s28, 0x2000
	s_nop 0
	global_load_lds_dwordx4 v[148:149], off
	s_waitcnt vmcnt(6)
	s_barrier
	v_mfma_f32_16x16x32_bf16 v[46:49], v[216:219], v[164:167], v[46:49]
	v_mfma_f32_16x16x32_bf16 v[42:45], v[224:227], v[164:167], v[42:45]
	v_mfma_f32_16x16x32_bf16 v[30:33], v[216:219], v[192:195], v[30:33]
	v_mfma_f32_16x16x32_bf16 v[26:29], v[224:227], v[192:195], v[26:29]
	v_mfma_f32_16x16x32_bf16 v[14:17], v[216:219], v[200:203], v[14:17]
	v_mfma_f32_16x16x32_bf16 v[10:13], v[224:227], v[200:203], v[10:13]
	v_mfma_f32_16x16x32_bf16 v[6:9], v[216:219], v[208:211], v[6:9]
	v_mfma_f32_16x16x32_bf16 v[2:5], v[224:227], v[208:211], v[2:5]
	v_mfma_f32_16x16x32_bf16 v[46:49], v[220:223], v[168:171], v[46:49]
	v_mfma_f32_16x16x32_bf16 v[42:45], v[228:231], v[168:171], v[42:45]
	v_mfma_f32_16x16x32_bf16 v[30:33], v[220:223], v[196:199], v[30:33]
	v_mfma_f32_16x16x32_bf16 v[26:29], v[228:231], v[196:199], v[26:29]
	v_mfma_f32_16x16x32_bf16 v[14:17], v[220:223], v[204:207], v[14:17]
	v_mfma_f32_16x16x32_bf16 v[10:13], v[228:231], v[204:207], v[10:13]
	v_mfma_f32_16x16x32_bf16 v[6:9], v[220:223], v[212:215], v[6:9]
	v_mfma_f32_16x16x32_bf16 v[2:5], v[228:231], v[212:215], v[2:5]
	s_add_i32 s55, s55, 2
	s_add_u32 s20, s20, 0x100
	s_addc_u32 s21, s21, 0
	s_add_u32 s22, s10, s20
	s_addc_u32 s23, s11, s21
	s_add_u32 s30, s22, 0x100
	s_addc_u32 s31, s23, 0
	s_add_u32 s56, s51, s20
	s_addc_u32 s57, s54, s21
	s_add_u32 s22, s22, 0x180
	s_addc_u32 s23, s23, 0
	s_add_i32 s58, 0, 0x10000
	v_add_u32_e32 v160, s58, v145
	s_cmp_gt_u32 s55, 13
	s_barrier
	s_cbranch_scc0 .LBB0_137
	v_lshl_or_b32 v140, s40, 8, v146
	v_lshl_add_u32 v148, s41, 8, v144
	v_ashrrev_i32_e32 v141, 31, v140
	v_lshl_add_u64 v[140:141], v[140:141], 1, s[0:1]
	v_cvt_pk_bf16_f32 v70, v70, v71
	v_cvt_pk_bf16_f32 v71, v72, v73
	v_cvt_pk_bf16_f32 v72, v66, v67
	v_add_u32_e32 v66, 0x80, v148
	v_mad_i64_i32 v[142:143], s[10:11], v148, s52, v[140:141]
	v_cvt_pk_bf16_f32 v110, v110, v111
	v_cvt_pk_bf16_f32 v111, v112, v113
	v_cvt_pk_bf16_f32 v112, v106, v107
	v_cvt_pk_bf16_f32 v113, v108, v109
	v_or_b32_e32 v106, 16, v148
	v_mad_i64_i32 v[66:67], s[10:11], v66, s52, v[140:141]
	v_cvt_pk_bf16_f32 v46, v46, v47
	v_cvt_pk_bf16_f32 v47, v48, v49
	v_cvt_pk_bf16_f32 v48, v42, v43
	v_cvt_pk_bf16_f32 v49, v44, v45
	v_add_u32_e32 v42, 0x90, v148
	flat_store_dwordx4 v[142:143], v[110:113] offset:256
	v_cvt_pk_bf16_f32 v94, v94, v95
	v_cvt_pk_bf16_f32 v95, v96, v97
	v_mad_i64_i32 v[110:111], s[10:11], v106, s52, v[140:141]
	v_cvt_pk_bf16_f32 v96, v90, v91
	v_cvt_pk_bf16_f32 v97, v92, v93
	v_or_b32_e32 v90, 32, v148
	flat_store_dwordx4 v[66:67], v[46:49] offset:256
	v_cvt_pk_bf16_f32 v30, v30, v31
	v_cvt_pk_bf16_f32 v31, v32, v33
	v_mad_i64_i32 v[46:47], s[10:11], v42, s52, v[140:141]
	v_cvt_pk_bf16_f32 v32, v26, v27
	v_cvt_pk_bf16_f32 v33, v28, v29
	v_add_u32_e32 v26, 0xa0, v148
	flat_store_dwordx4 v[110:111], v[94:97] offset:256
	v_cvt_pk_bf16_f32 v78, v78, v79
	v_cvt_pk_bf16_f32 v79, v80, v81
	v_mad_i64_i32 v[94:95], s[10:11], v90, s52, v[140:141]
	v_cvt_pk_bf16_f32 v80, v74, v75
	v_cvt_pk_bf16_f32 v81, v76, v77
	v_or_b32_e32 v74, 48, v148
	flat_store_dwordx4 v[46:47], v[30:33] offset:256
	v_cvt_pk_bf16_f32 v14, v14, v15
	v_cvt_pk_bf16_f32 v15, v16, v17
	v_mad_i64_i32 v[30:31], s[10:11], v26, s52, v[140:141]
	v_cvt_pk_bf16_f32 v16, v10, v11
	v_cvt_pk_bf16_f32 v17, v12, v13
	v_add_u32_e32 v10, 0xb0, v148
	flat_store_dwordx4 v[94:95], v[78:81] offset:256
	flat_store_dwordx4 v[30:31], v[14:17] offset:256
	v_cvt_pk_bf16_f32 v126, v126, v127
	v_mad_i64_i32 v[78:79], s[10:11], v74, s52, v[140:141]
	v_mad_i64_i32 v[14:15], s[10:11], v10, s52, v[140:141]
	v_cvt_pk_bf16_f32 v127, v128, v129
	v_cvt_pk_bf16_f32 v128, v122, v123
	v_cvt_pk_bf16_f32 v129, v124, v125
	v_cvt_pk_bf16_f32 v106, v118, v119
	v_cvt_pk_bf16_f32 v107, v120, v121
	v_cvt_pk_bf16_f32 v108, v114, v115
	v_cvt_pk_bf16_f32 v109, v116, v117
	v_cvt_pk_bf16_f32 v90, v102, v103
	v_cvt_pk_bf16_f32 v91, v104, v105
	v_cvt_pk_bf16_f32 v92, v98, v99
	v_cvt_pk_bf16_f32 v93, v100, v101
	v_cvt_pk_bf16_f32 v74, v86, v87
	v_cvt_pk_bf16_f32 v75, v88, v89
	v_cvt_pk_bf16_f32 v76, v82, v83
	v_cvt_pk_bf16_f32 v77, v84, v85
	v_cvt_pk_bf16_f32 v73, v68, v69
	v_cvt_pk_bf16_f32 v62, v62, v63
	v_cvt_pk_bf16_f32 v63, v64, v65
	v_cvt_pk_bf16_f32 v64, v58, v59
	v_cvt_pk_bf16_f32 v65, v60, v61
	v_cvt_pk_bf16_f32 v42, v54, v55
	v_cvt_pk_bf16_f32 v43, v56, v57
	v_cvt_pk_bf16_f32 v44, v50, v51
	v_cvt_pk_bf16_f32 v45, v52, v53
	v_cvt_pk_bf16_f32 v26, v38, v39
	v_cvt_pk_bf16_f32 v27, v40, v41
	v_cvt_pk_bf16_f32 v28, v34, v35
	v_cvt_pk_bf16_f32 v29, v36, v37
	v_cvt_pk_bf16_f32 v10, v22, v23
	v_cvt_pk_bf16_f32 v11, v24, v25
	v_cvt_pk_bf16_f32 v12, v18, v19
	v_cvt_pk_bf16_f32 v13, v20, v21
	v_cvt_pk_bf16_f32 v6, v6, v7
	v_cvt_pk_bf16_f32 v7, v8, v9
	v_cvt_pk_bf16_f32 v8, v2, v3
	v_cvt_pk_bf16_f32 v9, v4, v5
	s_and_b64 vcc, exec, s[8:9]
	s_mov_b32 s40, s6
	s_mov_b32 s41, s4
	s_mov_b64 s[20:21], s[14:15]
	s_mov_b64 s[10:11], s[12:13]
	flat_store_dwordx4 v[142:143], v[126:129]
	flat_store_dwordx4 v[110:111], v[106:109]
	flat_store_dwordx4 v[94:95], v[90:93]
	flat_store_dwordx4 v[78:79], v[74:77]
	flat_store_dwordx4 v[78:79], v[70:73] offset:256
	flat_store_dwordx4 v[66:67], v[62:65]
	flat_store_dwordx4 v[46:47], v[42:45]
	flat_store_dwordx4 v[30:31], v[26:29]
	flat_store_dwordx4 v[14:15], v[10:13]
	flat_store_dwordx4 v[14:15], v[6:9] offset:256
	s_cbranch_vccz .LBB0_134
	s_waitcnt vmcnt(0)
	s_cmpk_gt_u32 s2, 0xff
	s_cbranch_scc1 .LBB0_141
	s_barrier
